# v49 with the ff-in (w_in) GEMM tile loop re-placed: 44 bytes of never-executed padding so its main loop head sits at the same 64-byte phase as in v43
# speedup vs baseline: 1.0090x; 1.0073x over previous
; #define PG8_STAGE(bufoff, gbase, voff) do { _Pragma("unroll") for (int _i = 0; _i < 2; ++_i) \
;     __builtin_amdgcn_global_load_lds((const unsigned*)((const char*)(gbase) + (voff)[_i]), (PG8_LAS unsigned*)(lds + (bufoff) + ldsw + _i * 8192), 16, 0, 0); } while (0)
; #define PG8_WAIT_V(n) asm volatile("s_waitcnt vmcnt(" #n ")" ::: "memory")
; #define PG8_BAR __builtin_amdgcn_s_barrier()
; template <class Epi, bool SEQ>
; DEV void gemm_phase(PG8_LAS unsigned char* lds, const Gemm g, const Epi& E) {
;     ...
;   for (int i = 0; i < 2; ++i) { int R, C; stage_rc(tid * 16 + i * 8192, R, C); const int Rb = Epi::PERM ? ((R & ~31) + perm32(R & 31)) : R;
;     voffA[i] = (unsigned)(R * g.lda + C) * 2u; voffB[i] = (unsigned)(Rb * g.ldb + C) * 2u; }
;   const size_t kstep = (size_t)(BK * 2);
;   const size_t hstepA = (size_t)HALF * g.lda * 2, hstepB = (size_t)HALF * g.ldb * 2;
;   const size_t tstepA = 2 * hstepA, tstepB = 2 * hstepB;
;   const unsigned ldsw = (unsigned)wid * 1024u;
;   const int aoff = lds_byte(wr * 64 + fr, fq * 8), boff = lds_byte(wc * 32 + fr, fq * 8);
;     ...
;   PG8_STAGE(PG8_SB(0, 0), cB, voffB); PG8_STAGE(PG8_SB(0, 1), cB + hstepB, voffB); PG8_STAGE(PG8_SA(0, 0), cA, voffA); PG8_STAGE(PG8_SA(0, 1), cA + hstepA, voffA);
;   if (wr == 1) PG8_BAR;
;   PG8_WAIT_V(2); PG8_BAR;
;   PG8_STAGE(PG8_SB(1, 0), cB + kstep, voffB); PG8_STAGE(PG8_SA(1, 0), cA + kstep, voffA); PG8_STAGE(PG8_SB(1, 1), cB + hstepB + kstep, voffB);
;   PG8_WAIT_V(6); PG8_BAR;
.LBB0_489:
	s_lshl_b32 s4, s4, 5
	s_and_b32 s9, s4, 0x60
	s_add_i32 m0, s35, 0x18000
	v_lshl_add_u64 v[6:7], v[6:7], 0, s[10:11]
	s_lshl_b32 s8, s3, 13
	s_lshl_b32 s12, s9, 7
	s_waitcnt vmcnt(2)
	s_barrier
	global_load_lds_dwordx4 v[6:7], off
	v_lshl_add_u64 v[4:5], v[4:5], 0, s[10:11]
	s_add_i32 m0, s35, 0x1a000
	s_add_i32 s39, s35, 0x8000
	s_add_i32 s40, s35, 0xa000
	global_load_lds_dwordx4 v[4:5], off
	v_lshl_add_u64 v[0:1], v[0:1], 0, s[10:11]
	s_mov_b32 m0, s39
	s_add_u32 s4, s20, 0x40080
	global_load_lds_dwordx4 v[0:1], off
	v_lshl_add_u64 v[0:1], v[2:3], 0, s[10:11]
	s_mov_b32 m0, s40
	s_addc_u32 s5, s21, 0
	global_load_lds_dwordx4 v[0:1], off
	s_add_i32 m0, s35, 0x1c000
	v_lshl_add_u64 v[0:1], s[4:5], 0, v[168:169]
	global_load_lds_dwordx4 v[0:1], off
	v_lshl_add_u64 v[0:1], s[4:5], 0, v[132:133]
	s_add_i32 m0, s35, 0x1e000
	s_cmpk_lt_u32 s2, 0x100
	global_load_lds_dwordx4 v[0:1], off
	v_lshrrev_b32_e32 v1, 1, v8
	v_and_b32_e32 v1, 24, v1
	v_and_b32_e32 v0, 15, v8
	v_lshlrev_b32_e32 v2, 1, v1
	v_lshl_or_b32 v138, s3, 6, v0
	v_lshl_or_b32 v0, v0, 6, v2
	v_lshlrev_b32_e32 v2, 2, v8
	v_and_b32_e32 v2, 32, v2
	v_bitop3_b32 v3, v0, s8, v2 bitop3:0xde
	v_bitop3_b32 v139, v0, s12, v2 bitop3:0xde
	v_lshlrev_b32_e32 v0, 14, v9
	v_and_b32_e32 v0, 0xffff8000, v0
	v_or_b32_e32 v140, s9, v1
	v_lshl_add_u32 v0, v10, 11, v0
	v_and_b32_e32 v1, 1, v9
	v_lshl_or_b32 v0, v1, 6, v0
	v_lshl_add_u32 v134, v11, 1, v0
	v_lshlrev_b32_e32 v0, 14, v12
	v_and_b32_e32 v0, 0xffff8000, v0
	s_waitcnt vmcnt(6)
	v_lshl_add_u32 v0, v13, 11, v0
	v_and_b32_e32 v1, 1, v12
	v_lshl_or_b32 v0, v1, 6, v0
	s_cselect_b64 s[2:3], -1, 0
	v_mov_b32_e32 v135, v169
	v_lshl_add_u32 v136, v14, 1, v0
	v_mov_b32_e32 v137, v169
	s_mov_b32 s41, 0
	v_add_u32_e32 v141, 0, v3
	s_barrier
	s_branch .LBB0_492
	s_nop 0
	s_nop 0
	s_nop 0
	s_nop 0
	s_nop 0
	s_nop 0
	s_nop 0
	s_nop 0
	s_nop 0
	s_nop 0
	s_nop 0
